# GEMM1/GEMM2 loops: B-fragment LDS reads use one invariant base VGPR + immediate offsets (16 address VALU per trip removed)
# speedup vs baseline: 1.0063x; 1.0063x over previous
; #define LAS __attribute__((address_space(3)))
; #define GS_STAGE(bufoff, gbase, voff, step) do { \
;     __builtin_amdgcn_global_load_lds((const unsigned*)((const char*)(gbase) + (voff)), (LAS unsigned*)(lds + (bufoff) + ldsw), 16, 0, 0); \
;     __builtin_amdgcn_global_load_lds((const unsigned*)((const char*)(gbase) + (step) + (voff)), (LAS unsigned*)(lds + (bufoff) + ldsw + 8192), 16, 0, 0); } while (0)
; #define GS_WAIT_V(n) asm volatile("s_waitcnt vmcnt(" #n ")" ::: "memory")
; #define GS_BAR __builtin_amdgcn_s_barrier()
; template <bool PEEL, class Sched, class Epi>
; DI void gemm_stream(LAS unsigned char* lds, int K, long lda, long ldb, const Sched& S, const Epi& E) {
;   int tid_ = threadIdx.x; asm volatile("" : "+v"(tid_));
;   const int tid = tid_ & 511, wid = __builtin_amdgcn_readfirstlane(tid >> 6), lane = tid & 63, wr = wid >> 2, wc = wid & 3, fr = lane & 15, fq = lane >> 4;
;   const int nt = K / 64;
;   unsigned voffA, voffB; long stepB, halfB;
;   const long stepA = 64 * lda;
;   { int R_, C_; stage_rc(tid * 16, R_, C_); voffA = (unsigned)(R_ * lda + C_ * 2); }
;   const size_t kstep = 128, hstepA = (size_t)128 * lda;
;   const unsigned ldsw = (unsigned)wid * 1024u;
;   const int aoff = lds_byte(wr * 64 + fr, fq * 8), boff = lds_byte(wc * 32 + fr, fq * 8);
;     ...
;   GUnit cur, nxt; int ui = 0;
;   if (!S.next(0, cur)) return;
;   f32x4 acc[2][2][4][2];
; #pragma unroll
;   for (int a = 0; a < 2; ++a)
; #pragma unroll
;     for (int b = 0; b < 2; ++b)
; #pragma unroll
;       for (int m = 0; m < 4; ++m)
; #pragma unroll
;         for (int n = 0; n < 2; ++n) { acc[a][b][m][n] = (f32x4){0.f, 0.f, 0.f, 0.f}; asm volatile("" : "+v"(acc[a][b][m][n])); }
;   f16x8 At[4][2], B0[2][2], B1[2][2];
;   const char* cA = cur.A; const char* cB = cur.B;
;   GS_SETB(cur.bmode);
;   GS_STAGE(GS_SB(0, 0), cB, voffB, stepB); GS_STAGE(GS_SA(0, 0), cA, voffA, stepA); GS_STAGE(GS_SB(0, 1), (cB) + halfB, voffB, stepB); GS_STAGE(GS_SA(0, 1), cA + hstepA, voffA, stepA);
;   if (wr == 1) GS_BAR;
;   GS_WAIT_V(4); GS_BAR;
;   GS_STAGE(GS_SB(1, 0), cB + kstep, voffB, stepB); GS_STAGE(GS_SA(1, 0), cA + kstep, voffA, stepA); GS_STAGE(GS_SB(1, 1), (cB + kstep) + halfB, voffB, stepB);
;   if (PEEL) { GS_STAGE(GS_SA(1, 1), cA + kstep + hstepA, voffA, stepA); GS_WAIT_V(0); } else GS_WAIT_V(6);
;   GS_BAR;
.LBB0_212:
	s_mov_b64 s[14:15], 0x80
	s_add_i32 s63, s51, 0x18000
	v_lshl_add_u64 v[138:139], v[138:139], 0, s[14:15]
	s_mov_b32 m0, s63
	s_add_i32 s64, s51, 0x1a000
	s_waitcnt vmcnt(4)
	s_barrier
	global_load_lds_dwordx4 v[138:139], off
	v_lshl_add_u64 v[136:137], v[136:137], 0, s[14:15]
	s_mov_b32 m0, s64
	s_add_i32 s65, s51, 0x8000
	global_load_lds_dwordx4 v[136:137], off
	v_lshl_add_u64 v[136:137], v[130:131], 0, s[14:15]
	s_mov_b32 m0, s65
	s_mov_b64 s[16:17], 0x20080
	s_add_i32 s72, s51, 0xa000
	global_load_lds_dwordx4 v[136:137], off
	v_lshl_add_u64 v[130:131], v[130:131], 0, s[16:17]
	s_mov_b32 m0, s72
	s_add_i32 s73, s51, 0x1c000
	global_load_lds_dwordx4 v[130:131], off
	v_lshl_add_u64 v[130:131], v[134:135], 0, s[14:15]
	s_mov_b32 m0, s73
	s_add_i32 s74, s51, 0x1e000
	global_load_lds_dwordx4 v[130:131], off
	v_lshl_add_u64 v[130:131], v[132:133], 0, s[14:15]
	s_mov_b32 m0, s74
	v_bfe_u32 v132, v140, 4, 2
	global_load_lds_dwordx4 v[130:131], off
	v_and_b32_e32 v130, 15, v140
	v_lshlrev_b32_e32 v131, 4, v132
	v_lshl_or_b32 v153, s7, 6, v130
	v_lshl_or_b32 v130, v130, 6, v131
	v_lshlrev_b32_e32 v131, 2, v140
	s_and_b32 s6, s20, 3
	s_lshl_b32 s7, s7, 13
	v_and_b32_e32 v131, 32, v131
	v_bitop3_b32 v165, v130, s7, v131 bitop3:0xde
	s_lshl_b32 s75, s6, 5
	s_lshl_b32 s7, s6, 12
	s_lshl_b32 s26, s6, 6
	s_cmp_lg_u32 s6, 0
	s_cselect_b64 s[20:21], -1, 0
	s_cmp_eq_u32 s6, 0
	v_bitop3_b32 v168, v130, s7, v131 bitop3:0xde
	v_add_u32_e32 v254, 0x10000, v168
	s_cselect_b64 s[6:7], -1, 0
	v_cmp_ne_u32_e32 vcc, 3, v132
	s_and_b64 s[22:23], vcc, s[6:7]
	v_readlane_b32 s6, v255, 11
	v_lshlrev_b32_e32 v130, 5, v132
	v_mov_b32_e32 v131, v149
	v_readlane_b32 s7, v255, 12
	s_waitcnt vmcnt(6)
	v_lshlrev_b32_e32 v150, 3, v132
	v_lshlrev_b32_e32 v152, 2, v132
	v_lshl_add_u64 v[154:155], s[6:7], 0, v[130:131]
	v_readlane_b32 s6, v255, 13
	v_readlane_b32 s7, v255, 14
	s_and_b32 s76, s2, 7
	s_bfe_u32 s77, s2, 0x20003
	v_lshl_add_u64 v[156:157], s[6:7], 0, v[130:131]
	v_lshlrev_b32_e32 v130, 6, v132
	v_lshl_add_u64 v[158:159], s[6:7], 0, v[130:131]
	v_lshlrev_b32_e32 v130, 8, v140
	v_and_b32_e32 v130, 0x18000, v130
	v_lshlrev_b32_e32 v131, 11, v141
	v_or3_b32 v130, v143, v130, v131
	s_ashr_i32 s78, s2, 5
	v_add_u32_e32 v160, v130, v142
	v_mov_b32_e32 v161, v149
	s_add_i32 s79, s51, 0xc000
	s_add_i32 s80, s51, 0xe000
	s_movk_i32 s81, 0x3000
	s_mov_b32 s24, 0x3e0293ee
	s_movk_i32 s82, 0x180
	s_lshl_b32 s26, s26, 1
	s_movk_i32 s83, 0x60
	v_mov_b32_e32 v169, 0x3e000000
	s_mov_b32 s29, s5
	s_mov_b64 s[30:31], s[4:5]
	s_barrier
	s_branch .LBB0_214

.LBB0_254:
	ds_read_b128 v[130:133], v254
	ds_read_b128 v[134:137], v254 offset:1024
	ds_read_b128 v[138:141], v254 offset:2048
	ds_read_b128 v[142:145], v254 offset:3072
	s_add_u32 s94, s44, 0xfffc0080
	s_addc_u32 s95, s45, -1
	s_and_b64 s[46:47], s[46:47], exec
	s_cselect_b32 s95, s29, s95
	s_cselect_b32 s94, s43, s94
	s_cselect_b32 s47, s89, s92
	s_cselect_b32 s46, s90, s91
	s_mov_b32 m0, s79
	v_lshl_add_u64 v[162:163], s[44:45], 0, v[160:161]
	ds_read_b128 v[170:173], v165
	ds_read_b128 v[174:177], v165 offset:1024
	ds_read_b128 v[178:181], v165 offset:2048
	ds_read_b128 v[182:185], v165 offset:3072
	ds_read_b128 v[186:189], v165 offset:4096
	ds_read_b128 v[190:193], v165 offset:5120
	ds_read_b128 v[194:197], v165 offset:6144
	ds_read_b128 v[198:201], v165 offset:7168
	s_cmp_lg_u32 s93, -2
	s_cbranch_scc1 .Lpl_stage1
	s_cmp_gt_u32 s85, 1
	s_cbranch_scc1 .Lpl_skip1

; DI unsigned pk2(float a, float b) { typedef _Float16 h2 __attribute__((ext_vector_type(2))); h2 v; v[0] = (f16)a; v[1] = (f16)b; return __builtin_bit_cast(unsigned, v); }
;   DI void operator()(const f32x4 (&acc)[2][2][4][2], const GUnit& u, int wr, int wc, int fr, int fq) const {
;     ...
; #pragma unroll
;     for (int ai = 0; ai < 2; ++ai)
; #pragma unroll
;       for (int m = 0; m < 4; ++m) {
;         f16* zp = base + (size_t)(row0 + ai * 128 + m * 16) * ld + u.pn * 256 + 32 * wc + 8 * fq;
; #pragma unroll
;         for (int bj = 0; bj < 2; ++bj) {
;           f32x4 v0 = acc[ai][bj][m][0], v1 = acc[ai][bj][m][1];
;           if (seg == 5) { v0 *= QSCALE; v1 *= QSCALE; }
;           u32x4_ w; w.x = pk2(v0[0], v0[1]); w.y = pk2(v0[2], v0[3]); w.z = pk2(v1[0], v1[1]); w.w = pk2(v1[2], v1[3]);
;           __builtin_nontemporal_store(w, (u32x4_*)(zp + bj * 128));
;         }
.Lpl_skip1:
	s_waitcnt lgkmcnt(8)
	s_barrier
	s_waitcnt lgkmcnt(0)
	s_waitcnt lgkmcnt(0)
	v_mfma_f32_16x16x32_f16 v[58:61], v[130:133], v[170:173], v[58:61]
	v_mfma_f32_16x16x32_f16 v[62:65], v[138:141], v[170:173], v[62:65]
	v_mfma_f32_16x16x32_f16 v[50:53], v[130:133], v[178:181], v[50:53]
	v_mfma_f32_16x16x32_f16 v[54:57], v[138:141], v[178:181], v[54:57]
	v_mfma_f32_16x16x32_f16 v[42:45], v[130:133], v[186:189], v[42:45]
	v_mfma_f32_16x16x32_f16 v[46:49], v[138:141], v[186:189], v[46:49]
	v_mfma_f32_16x16x32_f16 v[26:29], v[130:133], v[194:197], v[26:29]
	v_mfma_f32_16x16x32_f16 v[30:33], v[138:141], v[194:197], v[30:33]
	v_mfma_f32_16x16x32_f16 v[58:61], v[134:137], v[174:177], v[58:61]
	v_mfma_f32_16x16x32_f16 v[62:65], v[142:145], v[174:177], v[62:65]
	v_mfma_f32_16x16x32_f16 v[50:53], v[134:137], v[182:185], v[50:53]
	v_mfma_f32_16x16x32_f16 v[54:57], v[142:145], v[182:185], v[54:57]
	v_mfma_f32_16x16x32_f16 v[42:45], v[134:137], v[190:193], v[42:45]
	v_mfma_f32_16x16x32_f16 v[46:49], v[142:145], v[190:193], v[46:49]
	v_mfma_f32_16x16x32_f16 v[26:29], v[134:137], v[198:201], v[26:29]
	v_mfma_f32_16x16x32_f16 v[30:33], v[142:145], v[198:201], v[30:33]
	s_barrier
	s_mov_b32 m0, s54
	ds_read_b128 v[202:205], v254 offset:16384
	ds_read_b128 v[206:209], v254 offset:17408
	s_add_u32 s96, s46, s30
	ds_read_b128 v[210:213], v254 offset:18432
	ds_read_b128 v[214:217], v254 offset:19456
	global_load_lds_dwordx4 v148, s[46:47]
	s_addc_u32 s97, s47, s31
	s_mov_b32 m0, s55
	v_lshl_add_u64 v[162:163], s[46:47], 0, v[148:149]
	global_load_lds_dwordx4 v148, s[96:97]
	s_barrier
	s_waitcnt lgkmcnt(0)
	v_lshl_add_u64 v[166:167], s[96:97], 0, v[148:149]
	s_waitcnt lgkmcnt(0)
	v_mfma_f32_16x16x32_f16 v[122:125], v[202:205], v[170:173], v[122:125]
	v_mfma_f32_16x16x32_f16 v[126:129], v[210:213], v[170:173], v[126:129]
	v_mfma_f32_16x16x32_f16 v[114:117], v[202:205], v[178:181], v[114:117]
	v_mfma_f32_16x16x32_f16 v[118:121], v[210:213], v[178:181], v[118:121]
	v_mfma_f32_16x16x32_f16 v[106:109], v[202:205], v[186:189], v[106:109]
	v_mfma_f32_16x16x32_f16 v[110:113], v[210:213], v[186:189], v[110:113]
	v_mfma_f32_16x16x32_f16 v[98:101], v[202:205], v[194:197], v[98:101]
	v_mfma_f32_16x16x32_f16 v[102:105], v[210:213], v[194:197], v[102:105]
	v_mfma_f32_16x16x32_f16 v[122:125], v[206:209], v[174:177], v[122:125]
	v_mfma_f32_16x16x32_f16 v[126:129], v[214:217], v[174:177], v[126:129]
	v_mfma_f32_16x16x32_f16 v[114:117], v[206:209], v[182:185], v[114:117]
	v_mfma_f32_16x16x32_f16 v[118:121], v[214:217], v[182:185], v[118:121]
	v_mfma_f32_16x16x32_f16 v[106:109], v[206:209], v[190:193], v[106:109]
	v_mfma_f32_16x16x32_f16 v[110:113], v[214:217], v[190:193], v[110:113]
	v_mfma_f32_16x16x32_f16 v[98:101], v[206:209], v[198:201], v[98:101]
	v_mfma_f32_16x16x32_f16 v[102:105], v[214:217], v[198:201], v[102:105]
	s_mov_b32 m0, s51
	v_lshl_add_u64 v[218:219], s[94:95], 0, v[146:147]
	s_barrier
	s_cmp_lg_u32 s100, 1
	s_cbranch_scc1 .Ldef_A_skip
	s_mov_b64 vcc, 0x30000
	v_cvt_pk_f16_f32 v242, v34, v35
	v_cvt_pk_f16_f32 v243, v36, v37
	v_cvt_pk_f16_f32 v244, v38, v39
	v_cvt_pk_f16_f32 v245, v40, v41
	global_store_dwordx4 v[240:241], v[242:245], off nt
	v_cvt_pk_f16_f32 v246, v18, v19
	v_cvt_pk_f16_f32 v247, v20, v21
	v_cvt_pk_f16_f32 v248, v22, v23
	v_cvt_pk_f16_f32 v249, v24, v25
	v_lshl_add_u64 v[250:251], v[240:241], 0, vcc
	global_store_dwordx4 v[250:251], v[246:249], off nt
	v_cvt_pk_f16_f32 v242, v10, v11
	v_cvt_pk_f16_f32 v243, v12, v13
	v_cvt_pk_f16_f32 v244, v14, v15
	v_cvt_pk_f16_f32 v245, v16, v17
	v_lshl_add_u64 v[252:253], v[250:251], 0, vcc
	global_store_dwordx4 v[252:253], v[242:245], off nt
	v_cvt_pk_f16_f32 v246, v2, v3
	v_cvt_pk_f16_f32 v247, v4, v5
	v_cvt_pk_f16_f32 v248, v6, v7
	v_cvt_pk_f16_f32 v249, v8, v9
	v_lshl_add_u64 v[250:251], v[252:253], 0, vcc
	global_store_dwordx4 v[250:251], v[246:249], off nt
	v_mov_b64_e32 v[2:3], 0
	v_mov_b64_e32 v[4:5], 0
	v_mov_b64_e32 v[6:7], 0
	v_mov_b64_e32 v[8:9], 0
	v_mov_b64_e32 v[10:11], 0
	v_mov_b64_e32 v[12:13], 0
	v_mov_b64_e32 v[14:15], 0
	v_mov_b64_e32 v[16:17], 0
	v_mov_b64_e32 v[18:19], 0
	v_mov_b64_e32 v[20:21], 0
	v_mov_b64_e32 v[22:23], 0
	v_mov_b64_e32 v[24:25], 0
	v_mov_b64_e32 v[34:35], 0
	v_mov_b64_e32 v[36:37], 0
	v_mov_b64_e32 v[38:39], 0
	v_mov_b64_e32 v[40:41], 0

.Lpl_wdone:
	s_barrier
	v_mfma_f32_16x16x32_f16 v[90:93], v[202:205], v[170:173], v[90:93]
	v_mfma_f32_16x16x32_f16 v[94:97], v[210:213], v[170:173], v[94:97]
	v_mfma_f32_16x16x32_f16 v[82:85], v[202:205], v[178:181], v[82:85]
	v_mfma_f32_16x16x32_f16 v[86:89], v[210:213], v[178:181], v[86:89]
	v_mfma_f32_16x16x32_f16 v[74:77], v[202:205], v[186:189], v[74:77]
	v_mfma_f32_16x16x32_f16 v[78:81], v[210:213], v[186:189], v[78:81]
	v_mfma_f32_16x16x32_f16 v[70:73], v[202:205], v[194:197], v[70:73]
	v_mfma_f32_16x16x32_f16 v[66:69], v[210:213], v[194:197], v[66:69]
	v_mfma_f32_16x16x32_f16 v[90:93], v[206:209], v[174:177], v[90:93]
	v_mfma_f32_16x16x32_f16 v[94:97], v[214:217], v[174:177], v[94:97]
	v_mfma_f32_16x16x32_f16 v[82:85], v[206:209], v[182:185], v[82:85]
	v_mfma_f32_16x16x32_f16 v[86:89], v[214:217], v[182:185], v[86:89]
	v_mfma_f32_16x16x32_f16 v[74:77], v[206:209], v[190:193], v[74:77]
	v_mfma_f32_16x16x32_f16 v[78:81], v[214:217], v[190:193], v[78:81]
	v_mfma_f32_16x16x32_f16 v[70:73], v[206:209], v[198:201], v[70:73]
	v_mfma_f32_16x16x32_f16 v[66:69], v[214:217], v[198:201], v[66:69]
	s_barrier
	ds_read_b128 v[130:133], v254 offset:32768
	ds_read_b128 v[134:137], v254 offset:33792
	ds_read_b128 v[138:141], v254 offset:34816
	ds_read_b128 v[142:145], v254 offset:35840
	s_mov_b32 m0, s61
	v_lshl_add_u64 v[202:203], v[218:219], 0, s[8:9]
	ds_read_b128 v[170:173], v165 offset:32768
	ds_read_b128 v[174:177], v165 offset:33792
	ds_read_b128 v[178:181], v165 offset:34816
	ds_read_b128 v[182:185], v165 offset:35840
	ds_read_b128 v[186:189], v165 offset:36864
	ds_read_b128 v[190:193], v165 offset:37888
	ds_read_b128 v[194:197], v165 offset:38912
	ds_read_b128 v[198:201], v165 offset:39936
	global_load_lds_dwordx4 v[202:203], off
	v_lshl_add_u64 v[202:203], v[218:219], 0, s[12:13]
	s_mov_b32 m0, s62
	s_nop 0
	global_load_lds_dwordx4 v[202:203], off
	s_waitcnt lgkmcnt(8)
	s_barrier
	s_waitcnt lgkmcnt(0)
	s_waitcnt lgkmcnt(0)
	v_mfma_f32_16x16x32_f16 v[58:61], v[130:133], v[170:173], v[58:61]
	v_mfma_f32_16x16x32_f16 v[62:65], v[138:141], v[170:173], v[62:65]
	v_mfma_f32_16x16x32_f16 v[50:53], v[130:133], v[178:181], v[50:53]
	v_mfma_f32_16x16x32_f16 v[54:57], v[138:141], v[178:181], v[54:57]
	v_mfma_f32_16x16x32_f16 v[42:45], v[130:133], v[186:189], v[42:45]
	v_mfma_f32_16x16x32_f16 v[46:49], v[138:141], v[186:189], v[46:49]
	v_mfma_f32_16x16x32_f16 v[26:29], v[130:133], v[194:197], v[26:29]
	v_mfma_f32_16x16x32_f16 v[30:33], v[138:141], v[194:197], v[30:33]
	v_mfma_f32_16x16x32_f16 v[58:61], v[134:137], v[174:177], v[58:61]
	v_mfma_f32_16x16x32_f16 v[62:65], v[142:145], v[174:177], v[62:65]
	v_mfma_f32_16x16x32_f16 v[50:53], v[134:137], v[182:185], v[50:53]
	v_mfma_f32_16x16x32_f16 v[54:57], v[142:145], v[182:185], v[54:57]
	v_mfma_f32_16x16x32_f16 v[42:45], v[134:137], v[190:193], v[42:45]
	v_mfma_f32_16x16x32_f16 v[46:49], v[142:145], v[190:193], v[46:49]
	v_mfma_f32_16x16x32_f16 v[26:29], v[134:137], v[198:201], v[26:29]
	v_mfma_f32_16x16x32_f16 v[30:33], v[142:145], v[198:201], v[30:33]
	s_barrier
	s_mov_b32 m0, s63
	ds_read_b128 v[202:205], v254 offset:49152
	ds_read_b128 v[206:209], v254 offset:50176
	v_lshl_add_u64 v[162:163], v[162:163], 0, s[14:15]
	ds_read_b128 v[210:213], v254 offset:51200
	ds_read_b128 v[214:217], v254 offset:52224
	global_load_lds_dwordx4 v[162:163], off
	v_lshl_add_u64 v[162:163], v[166:167], 0, s[14:15]
	s_mov_b32 m0, s64
	s_nop 0
	global_load_lds_dwordx4 v[162:163], off
	s_barrier
; template <bool PEEL, class Sched, class Epi>
; DI void gemm_stream(LAS unsigned char* lds, int K, long lda, long ldb, const Sched& S, const Epi& E) {
;     ...
;     if (PEEL) { GS_TRIP(0, 1); for (int t = 2; t < nt; t += 2) { GS_TRIP(t, 0); } }
	s_waitcnt lgkmcnt(0)
	s_waitcnt lgkmcnt(0)
	v_mfma_f32_16x16x32_f16 v[122:125], v[202:205], v[170:173], v[122:125]
	v_mfma_f32_16x16x32_f16 v[126:129], v[210:213], v[170:173], v[126:129]
	v_mfma_f32_16x16x32_f16 v[114:117], v[202:205], v[178:181], v[114:117]
	v_mfma_f32_16x16x32_f16 v[118:121], v[210:213], v[178:181], v[118:121]
	v_mfma_f32_16x16x32_f16 v[106:109], v[202:205], v[186:189], v[106:109]
	v_mfma_f32_16x16x32_f16 v[110:113], v[210:213], v[186:189], v[110:113]
	v_mfma_f32_16x16x32_f16 v[98:101], v[202:205], v[194:197], v[98:101]
	v_mfma_f32_16x16x32_f16 v[102:105], v[210:213], v[194:197], v[102:105]
	v_mfma_f32_16x16x32_f16 v[122:125], v[206:209], v[174:177], v[122:125]
	v_mfma_f32_16x16x32_f16 v[126:129], v[214:217], v[174:177], v[126:129]
	v_mfma_f32_16x16x32_f16 v[114:117], v[206:209], v[182:185], v[114:117]
	v_mfma_f32_16x16x32_f16 v[118:121], v[214:217], v[182:185], v[118:121]
	v_mfma_f32_16x16x32_f16 v[106:109], v[206:209], v[190:193], v[106:109]
	v_mfma_f32_16x16x32_f16 v[110:113], v[214:217], v[190:193], v[110:113]
	v_mfma_f32_16x16x32_f16 v[98:101], v[206:209], v[198:201], v[98:101]
	v_mfma_f32_16x16x32_f16 v[102:105], v[214:217], v[198:201], v[102:105]
	s_mov_b32 m0, s65
	v_lshl_add_u64 v[162:163], v[218:219], 0, s[14:15]
	s_barrier
	ds_read_b128 v[170:173], v165 offset:49152
	ds_read_b128 v[174:177], v165 offset:50176
	ds_read_b128 v[178:181], v165 offset:51200
	ds_read_b128 v[182:185], v165 offset:52224
	ds_read_b128 v[186:189], v165 offset:53248
	ds_read_b128 v[190:193], v165 offset:54272
	ds_read_b128 v[194:197], v165 offset:55296
	ds_read_b128 v[198:201], v165 offset:56320
	global_load_lds_dwordx4 v[162:163], off
	v_lshl_add_u64 v[162:163], v[218:219], 0, s[16:17]
	s_mov_b32 m0, s72
	s_nop 0
	global_load_lds_dwordx4 v[162:163], off
	s_barrier
	s_waitcnt lgkmcnt(0)
	s_waitcnt lgkmcnt(0)
	v_mfma_f32_16x16x32_f16 v[34:37], v[130:133], v[170:173], v[34:37]
	v_mfma_f32_16x16x32_f16 v[38:41], v[138:141], v[170:173], v[38:41]
	v_mfma_f32_16x16x32_f16 v[18:21], v[130:133], v[178:181], v[18:21]
	v_mfma_f32_16x16x32_f16 v[22:25], v[138:141], v[178:181], v[22:25]
	v_mfma_f32_16x16x32_f16 v[10:13], v[130:133], v[186:189], v[10:13]
	v_mfma_f32_16x16x32_f16 v[14:17], v[138:141], v[186:189], v[14:17]
	v_mfma_f32_16x16x32_f16 v[2:5], v[130:133], v[194:197], v[2:5]
	v_mfma_f32_16x16x32_f16 v[6:9], v[138:141], v[194:197], v[6:9]
	v_mfma_f32_16x16x32_f16 v[34:37], v[134:137], v[174:177], v[34:37]
	v_mfma_f32_16x16x32_f16 v[38:41], v[142:145], v[174:177], v[38:41]
	v_mfma_f32_16x16x32_f16 v[18:21], v[134:137], v[182:185], v[18:21]
	v_mfma_f32_16x16x32_f16 v[22:25], v[142:145], v[182:185], v[22:25]
	v_mfma_f32_16x16x32_f16 v[10:13], v[134:137], v[190:193], v[10:13]
	v_mfma_f32_16x16x32_f16 v[14:17], v[142:145], v[190:193], v[14:17]
	v_mfma_f32_16x16x32_f16 v[2:5], v[134:137], v[198:201], v[2:5]
	v_mfma_f32_16x16x32_f16 v[6:9], v[142:145], v[198:201], v[6:9]
	s_barrier
	s_mov_b32 m0, s73
	v_lshl_add_u64 v[130:131], v[220:221], 0, s[14:15]
	global_load_lds_dwordx4 v[130:131], off
	v_lshl_add_u64 v[130:131], v[222:223], 0, s[14:15]
	s_mov_b32 m0, s74
	s_nop 0
	global_load_lds_dwordx4 v[130:131], off
	s_waitcnt vmcnt(6)
	s_barrier
	s_cmp_lg_u32 s93, 12
	s_cbranch_scc1 .Lpl_skip8
	s_and_b64 vcc, exec, s[6:7]
	s_cbranch_vccz .Lpl_skip8
	s_add_u32 s94, s43, 0x40080
	s_addc_u32 s95, s29, 0
	s_mov_b32 m0, s79
	v_lshl_add_u64 v[130:131], s[94:95], 0, v[160:161]
	global_load_lds_dwordx4 v[130:131], off
	v_lshl_add_u64 v[130:131], v[130:131], 0, s[0:1]
	s_mov_b32 m0, s80
	s_nop 0
	global_load_lds_dwordx4 v[130:131], off

; #define LAS __attribute__((address_space(3)))
; #define GS_STAGE(bufoff, gbase, voff, step) do { \
;     __builtin_amdgcn_global_load_lds((const unsigned*)((const char*)(gbase) + (voff)), (LAS unsigned*)(lds + (bufoff) + ldsw), 16, 0, 0); \
;     __builtin_amdgcn_global_load_lds((const unsigned*)((const char*)(gbase) + (step) + (voff)), (LAS unsigned*)(lds + (bufoff) + ldsw + 8192), 16, 0, 0); } while (0)
; #define GS_WAIT_V(n) asm volatile("s_waitcnt vmcnt(" #n ")" ::: "memory")
; #define GS_BAR __builtin_amdgcn_s_barrier()
; template <bool PEEL, class Sched, class Epi>
; DI void gemm_stream(LAS unsigned char* lds, int K, long lda, long ldb, const Sched& S, const Epi& E) {
;   int tid_ = threadIdx.x; asm volatile("" : "+v"(tid_));
;   const int tid = tid_ & 511, wid = __builtin_amdgcn_readfirstlane(tid >> 6), lane = tid & 63, wr = wid >> 2, wc = wid & 3, fr = lane & 15, fq = lane >> 4;
;   const int nt = K / 64;
;   unsigned voffA, voffB; long stepB, halfB;
;   const long stepA = 64 * lda;
;   { int R_, C_; stage_rc(tid * 16, R_, C_); voffA = (unsigned)(R_ * lda + C_ * 2); }
;   const size_t kstep = 128, hstepA = (size_t)128 * lda;
;   const unsigned ldsw = (unsigned)wid * 1024u;
;   const int aoff = lds_byte(wr * 64 + fr, fq * 8), boff = lds_byte(wc * 32 + fr, fq * 8);
;     ...
;   GUnit cur, nxt; int ui = 0;
;   if (!S.next(0, cur)) return;
;   f32x4 acc[2][2][4][2];
; #pragma unroll
;   for (int a = 0; a < 2; ++a)
; #pragma unroll
;     for (int b = 0; b < 2; ++b)
; #pragma unroll
;       for (int m = 0; m < 4; ++m)
; #pragma unroll
;         for (int n = 0; n < 2; ++n) { acc[a][b][m][n] = (f32x4){0.f, 0.f, 0.f, 0.f}; asm volatile("" : "+v"(acc[a][b][m][n])); }
;   f16x8 At[4][2], B0[2][2], B1[2][2];
;   const char* cA = cur.A; const char* cB = cur.B;
;   GS_SETB(cur.bmode);
;   GS_STAGE(GS_SB(0, 0), cB, voffB, stepB); GS_STAGE(GS_SA(0, 0), cA, voffA, stepA); GS_STAGE(GS_SB(0, 1), (cB) + halfB, voffB, stepB); GS_STAGE(GS_SA(0, 1), cA + hstepA, voffA, stepA);
;   if (wr == 1) GS_BAR;
;   GS_WAIT_V(4); GS_BAR;
;   GS_STAGE(GS_SB(1, 0), cB + kstep, voffB, stepB); GS_STAGE(GS_SA(1, 0), cA + kstep, voffA, stepA); GS_STAGE(GS_SB(1, 1), (cB + kstep) + halfB, voffB, stepB);
;   if (PEEL) { GS_STAGE(GS_SA(1, 1), cA + kstep + hstepA, voffA, stepA); GS_WAIT_V(0); } else GS_WAIT_V(6);
;   GS_BAR;
.LBB0_834:
	s_mov_b64 s[24:25], 0x80
	s_add_i32 s64, s56, 0x18000
	v_lshl_add_u64 v[140:141], v[134:135], 0, s[24:25]
	s_mov_b32 m0, s64
	s_mov_b64 s[26:27], 0x40080
	s_add_i32 s65, s56, 0x1a000
	s_waitcnt vmcnt(4)
	s_barrier
	global_load_lds_dwordx4 v[140:141], off
	v_lshl_add_u64 v[140:141], v[134:135], 0, s[26:27]
	s_mov_b32 m0, s65
	s_add_i32 s72, s56, 0x8000
	global_load_lds_dwordx4 v[140:141], off
	v_lshl_add_u64 v[140:141], v[136:137], 0, s[24:25]
	s_mov_b32 m0, s72
	s_mov_b64 s[28:29], 0xc0080
	s_add_i32 s73, s56, 0xa000
	global_load_lds_dwordx4 v[140:141], off
	v_lshl_add_u64 v[136:137], v[136:137], 0, s[28:29]
	s_mov_b32 m0, s73
	s_mov_b64 s[30:31], 0x80080
	s_add_i32 s74, s56, 0x1c000
	global_load_lds_dwordx4 v[136:137], off
	v_lshl_add_u64 v[136:137], v[134:135], 0, s[30:31]
	s_mov_b32 m0, s74
	s_add_i32 s75, s56, 0x1e000
	global_load_lds_dwordx4 v[136:137], off
	v_lshl_add_u64 v[134:135], v[134:135], 0, s[28:29]
	s_mov_b32 m0, s75
	s_lshl_b32 s4, s2, 3
	global_load_lds_dwordx4 v[134:135], off
	v_bfe_u32 v135, v138, 4, 2
	v_and_b32_e32 v134, 15, v138
	v_lshlrev_b32_e32 v137, 4, v135
	v_lshl_or_b32 v140, s1, 6, v134
	v_lshl_or_b32 v134, v134, 6, v137
	v_lshlrev_b32_e32 v137, 2, v138
	s_and_b32 s76, s0, 3
	s_lshl_b32 s0, s1, 13
	v_and_b32_e32 v137, 32, v137
	s_waitcnt vmcnt(6)
	s_and_b32 s4, s4, 56
	s_bfe_u32 s6, s2, 0x30003
	v_lshlrev_b32_e32 v136, 3, v135
	v_bitop3_b32 v141, v134, s0, v137 bitop3:0xde
	s_lshl_b32 s0, s76, 12
	s_or_b32 s4, s4, s6
	v_bitop3_b32 v142, v134, s0, v137 bitop3:0xde
	v_add_u32_e32 v254, 0x10000, v142
	v_lshl_or_b32 v143, s76, 5, v136
	v_cmp_eq_u32_e64 s[0:1], 0, v135
	s_or_b32 s77, s4, 64
	s_ashr_i32 s78, s2, 6
	v_add3_u32 v134, v145, v144, v139
	v_mov_b32_e32 v135, v133
	s_add_i32 s79, s56, 0xc000
	s_add_i32 s80, s56, 0xe000
	s_mov_b32 s4, 0
	s_barrier
	s_branch .LBB0_836

.LBB0_843:
	ds_read_b128 v[136:139], v254
	ds_read_b128 v[144:147], v254 offset:1024
	ds_read_b128 v[148:151], v254 offset:2048
	ds_read_b128 v[152:155], v254 offset:3072
	s_add_u32 s86, s44, 0xffe80080
	s_addc_u32 s87, s45, -1
	s_and_b64 s[46:47], s[46:47], exec
	s_cselect_b32 s47, s4, s87
	s_cselect_b32 s46, s43, s86
	s_cselect_b32 s87, s48, s84
	s_cselect_b32 s86, s50, s51
	s_mov_b32 m0, s79
	v_lshl_add_u64 v[188:189], s[44:45], 0, v[134:135]
	ds_read_b128 v[156:159], v141
	ds_read_b128 v[160:163], v141 offset:1024
	ds_read_b128 v[164:167], v141 offset:2048
	ds_read_b128 v[168:171], v141 offset:3072
	ds_read_b128 v[172:175], v141 offset:4096
	ds_read_b128 v[176:179], v141 offset:5120
	ds_read_b128 v[180:183], v141 offset:6144
	ds_read_b128 v[184:187], v141 offset:7168
	global_load_lds_dwordx4 v[188:189], off
	v_lshl_add_u64 v[188:189], v[188:189], 0, s[16:17]
	s_mov_b32 m0, s80
	s_nop 0
	global_load_lds_dwordx4 v[188:189], off
	s_waitcnt lgkmcnt(8)
	s_barrier
	s_waitcnt lgkmcnt(0)
	s_waitcnt lgkmcnt(0)
	v_mfma_f32_16x16x32_f16 v[118:121], v[136:139], v[156:159], v[118:121]
	v_mfma_f32_16x16x32_f16 v[114:117], v[148:151], v[156:159], v[114:117]
	v_mfma_f32_16x16x32_f16 v[102:105], v[136:139], v[164:167], v[102:105]
	v_mfma_f32_16x16x32_f16 v[98:101], v[148:151], v[164:167], v[98:101]
	v_mfma_f32_16x16x32_f16 v[86:89], v[136:139], v[172:175], v[86:89]
	v_mfma_f32_16x16x32_f16 v[82:85], v[148:151], v[172:175], v[82:85]
	v_mfma_f32_16x16x32_f16 v[66:69], v[136:139], v[180:183], v[66:69]
	v_mfma_f32_16x16x32_f16 v[54:57], v[148:151], v[180:183], v[54:57]
	v_mfma_f32_16x16x32_f16 v[118:121], v[144:147], v[160:163], v[118:121]
	v_mfma_f32_16x16x32_f16 v[114:117], v[152:155], v[160:163], v[114:117]
	v_mfma_f32_16x16x32_f16 v[102:105], v[144:147], v[168:171], v[102:105]
	v_mfma_f32_16x16x32_f16 v[98:101], v[152:155], v[168:171], v[98:101]
	v_mfma_f32_16x16x32_f16 v[86:89], v[144:147], v[176:179], v[86:89]
	v_mfma_f32_16x16x32_f16 v[82:85], v[152:155], v[176:179], v[82:85]
	v_mfma_f32_16x16x32_f16 v[66:69], v[144:147], v[184:187], v[66:69]
	v_mfma_f32_16x16x32_f16 v[54:57], v[152:155], v[184:187], v[54:57]
	s_barrier
	s_mov_b32 m0, s57
	v_lshl_add_u64 v[204:205], s[86:87], 0, v[132:133]
	ds_read_b128 v[188:191], v254 offset:16384
	ds_read_b128 v[192:195], v254 offset:17408
	ds_read_b128 v[196:199], v254 offset:18432
	ds_read_b128 v[200:203], v254 offset:19456
	global_load_lds_dwordx4 v132, s[86:87]
	v_lshl_add_u64 v[206:207], v[204:205], 0, s[14:15]
	s_mov_b32 m0, s58
	s_nop 0
	global_load_lds_dwordx4 v[206:207], off
	s_barrier
	s_waitcnt lgkmcnt(0)
	s_waitcnt lgkmcnt(0)
	v_mfma_f32_16x16x32_f16 v[122:125], v[188:191], v[156:159], v[122:125]
	v_mfma_f32_16x16x32_f16 v[126:129], v[196:199], v[156:159], v[126:129]
	v_mfma_f32_16x16x32_f16 v[106:109], v[188:191], v[164:167], v[106:109]
	v_mfma_f32_16x16x32_f16 v[110:113], v[196:199], v[164:167], v[110:113]
	v_mfma_f32_16x16x32_f16 v[90:93], v[188:191], v[172:175], v[90:93]
	v_mfma_f32_16x16x32_f16 v[94:97], v[196:199], v[172:175], v[94:97]
	v_mfma_f32_16x16x32_f16 v[74:77], v[188:191], v[180:183], v[74:77]
	v_mfma_f32_16x16x32_f16 v[78:81], v[196:199], v[180:183], v[78:81]
	v_mfma_f32_16x16x32_f16 v[122:125], v[192:195], v[160:163], v[122:125]
	v_mfma_f32_16x16x32_f16 v[126:129], v[200:203], v[160:163], v[126:129]
	v_mfma_f32_16x16x32_f16 v[106:109], v[192:195], v[168:171], v[106:109]
	v_mfma_f32_16x16x32_f16 v[110:113], v[200:203], v[168:171], v[110:113]
	v_mfma_f32_16x16x32_f16 v[90:93], v[192:195], v[176:179], v[90:93]
	v_mfma_f32_16x16x32_f16 v[94:97], v[200:203], v[176:179], v[94:97]
	v_mfma_f32_16x16x32_f16 v[74:77], v[192:195], v[184:187], v[74:77]
	v_mfma_f32_16x16x32_f16 v[78:81], v[200:203], v[184:187], v[78:81]
	s_mov_b32 m0, s56
	v_lshl_add_u64 v[206:207], s[46:47], 0, v[130:131]
	s_barrier
	ds_read_b128 v[156:159], v141 offset:16384
	ds_read_b128 v[160:163], v141 offset:17408
	ds_read_b128 v[164:167], v141 offset:18432
	ds_read_b128 v[168:171], v141 offset:19456
	ds_read_b128 v[172:175], v141 offset:20480
	ds_read_b128 v[176:179], v141 offset:21504
	ds_read_b128 v[180:183], v141 offset:22528
	ds_read_b128 v[184:187], v141 offset:23552
	global_load_lds_dwordx4 v[206:207], off
	v_lshl_add_u64 v[208:209], v[206:207], 0, s[16:17]
	s_mov_b32 m0, s59
	s_nop 0
	global_load_lds_dwordx4 v[208:209], off
	s_barrier
	s_waitcnt lgkmcnt(0)
	s_waitcnt lgkmcnt(0)
	v_mfma_f32_16x16x32_f16 v[58:61], v[136:139], v[156:159], v[58:61]
	v_mfma_f32_16x16x32_f16 v[50:53], v[148:151], v[156:159], v[50:53]
	v_mfma_f32_16x16x32_f16 v[38:41], v[136:139], v[164:167], v[38:41]
	v_mfma_f32_16x16x32_f16 v[34:37], v[148:151], v[164:167], v[34:37]
	v_mfma_f32_16x16x32_f16 v[22:25], v[136:139], v[172:175], v[22:25]
	v_mfma_f32_16x16x32_f16 v[18:21], v[148:151], v[172:175], v[18:21]
	v_mfma_f32_16x16x32_f16 v[10:13], v[136:139], v[180:183], v[10:13]
	v_mfma_f32_16x16x32_f16 v[6:9], v[148:151], v[180:183], v[6:9]
	v_mfma_f32_16x16x32_f16 v[58:61], v[144:147], v[160:163], v[58:61]
	v_mfma_f32_16x16x32_f16 v[50:53], v[152:155], v[160:163], v[50:53]
	v_mfma_f32_16x16x32_f16 v[38:41], v[144:147], v[168:171], v[38:41]
	v_mfma_f32_16x16x32_f16 v[34:37], v[152:155], v[168:171], v[34:37]
	v_mfma_f32_16x16x32_f16 v[22:25], v[144:147], v[176:179], v[22:25]
	v_mfma_f32_16x16x32_f16 v[18:21], v[152:155], v[176:179], v[18:21]
	v_mfma_f32_16x16x32_f16 v[10:13], v[144:147], v[184:187], v[10:13]
	v_mfma_f32_16x16x32_f16 v[6:9], v[152:155], v[184:187], v[6:9]
	s_barrier
	s_mov_b32 m0, s60
	v_lshl_add_u64 v[136:137], v[204:205], 0, s[18:19]
	global_load_lds_dwordx4 v[136:137], off
	v_lshl_add_u64 v[136:137], v[204:205], 0, s[16:17]
	s_mov_b32 m0, s61
	s_nop 0
	global_load_lds_dwordx4 v[136:137], off
	s_waitcnt vmcnt(6)
	s_barrier
	v_mfma_f32_16x16x32_f16 v[62:65], v[188:191], v[156:159], v[62:65]
	v_mfma_f32_16x16x32_f16 v[70:73], v[196:199], v[156:159], v[70:73]
	v_mfma_f32_16x16x32_f16 v[42:45], v[188:191], v[164:167], v[42:45]
	v_mfma_f32_16x16x32_f16 v[46:49], v[196:199], v[164:167], v[46:49]
	v_mfma_f32_16x16x32_f16 v[26:29], v[188:191], v[172:175], v[26:29]
	v_mfma_f32_16x16x32_f16 v[30:33], v[196:199], v[172:175], v[30:33]
	v_mfma_f32_16x16x32_f16 v[14:17], v[188:191], v[180:183], v[14:17]
	v_mfma_f32_16x16x32_f16 v[2:5], v[196:199], v[180:183], v[2:5]
	v_mfma_f32_16x16x32_f16 v[62:65], v[192:195], v[160:163], v[62:65]
	v_mfma_f32_16x16x32_f16 v[70:73], v[200:203], v[160:163], v[70:73]
	v_mfma_f32_16x16x32_f16 v[42:45], v[192:195], v[168:171], v[42:45]
	v_mfma_f32_16x16x32_f16 v[46:49], v[200:203], v[168:171], v[46:49]
	v_mfma_f32_16x16x32_f16 v[26:29], v[192:195], v[176:179], v[26:29]
	v_mfma_f32_16x16x32_f16 v[30:33], v[200:203], v[176:179], v[30:33]
	v_mfma_f32_16x16x32_f16 v[14:17], v[192:195], v[184:187], v[14:17]
	v_mfma_f32_16x16x32_f16 v[2:5], v[200:203], v[184:187], v[2:5]
	s_barrier
	ds_read_b128 v[136:139], v254 offset:32768
	ds_read_b128 v[144:147], v254 offset:33792
	ds_read_b128 v[148:151], v254 offset:34816
	ds_read_b128 v[152:155], v254 offset:35840
	s_mov_b32 m0, s62
	v_lshl_add_u64 v[188:189], v[206:207], 0, s[20:21]
	ds_read_b128 v[156:159], v141 offset:32768
	ds_read_b128 v[160:163], v141 offset:33792
	ds_read_b128 v[164:167], v141 offset:34816
	ds_read_b128 v[168:171], v141 offset:35840
	ds_read_b128 v[172:175], v141 offset:36864
	ds_read_b128 v[176:179], v141 offset:37888
	ds_read_b128 v[180:183], v141 offset:38912
	ds_read_b128 v[184:187], v141 offset:39936
	global_load_lds_dwordx4 v[188:189], off
	v_lshl_add_u64 v[188:189], v[206:207], 0, s[22:23]
	s_mov_b32 m0, s63
	s_nop 0
	global_load_lds_dwordx4 v[188:189], off
	s_waitcnt lgkmcnt(8)
	s_barrier
	s_waitcnt lgkmcnt(0)
	s_waitcnt lgkmcnt(0)
	v_mfma_f32_16x16x32_f16 v[118:121], v[136:139], v[156:159], v[118:121]
	v_mfma_f32_16x16x32_f16 v[114:117], v[148:151], v[156:159], v[114:117]
	v_mfma_f32_16x16x32_f16 v[102:105], v[136:139], v[164:167], v[102:105]
	v_mfma_f32_16x16x32_f16 v[98:101], v[148:151], v[164:167], v[98:101]
	v_mfma_f32_16x16x32_f16 v[86:89], v[136:139], v[172:175], v[86:89]
	v_mfma_f32_16x16x32_f16 v[82:85], v[148:151], v[172:175], v[82:85]
	v_mfma_f32_16x16x32_f16 v[66:69], v[136:139], v[180:183], v[66:69]
	v_mfma_f32_16x16x32_f16 v[54:57], v[148:151], v[180:183], v[54:57]
	v_mfma_f32_16x16x32_f16 v[118:121], v[144:147], v[160:163], v[118:121]
	v_mfma_f32_16x16x32_f16 v[114:117], v[152:155], v[160:163], v[114:117]
	v_mfma_f32_16x16x32_f16 v[102:105], v[144:147], v[168:171], v[102:105]
	v_mfma_f32_16x16x32_f16 v[98:101], v[152:155], v[168:171], v[98:101]
	v_mfma_f32_16x16x32_f16 v[86:89], v[144:147], v[176:179], v[86:89]
	v_mfma_f32_16x16x32_f16 v[82:85], v[152:155], v[176:179], v[82:85]
	v_mfma_f32_16x16x32_f16 v[66:69], v[144:147], v[184:187], v[66:69]
	v_mfma_f32_16x16x32_f16 v[54:57], v[152:155], v[184:187], v[54:57]
	s_barrier
	s_mov_b32 m0, s64
	v_lshl_add_u64 v[208:209], v[204:205], 0, s[24:25]
	ds_read_b128 v[188:191], v254 offset:49152
	ds_read_b128 v[192:195], v254 offset:50176
	ds_read_b128 v[196:199], v254 offset:51200
	ds_read_b128 v[200:203], v254 offset:52224
	global_load_lds_dwordx4 v[208:209], off
	v_lshl_add_u64 v[208:209], v[204:205], 0, s[26:27]
	s_mov_b32 m0, s65
	s_nop 0
	global_load_lds_dwordx4 v[208:209], off
	s_barrier
; template <bool PEEL, class Sched, class Epi>
; DI void gemm_stream(LAS unsigned char* lds, int K, long lda, long ldb, const Sched& S, const Epi& E) {
;     ...
;     if (PEEL) { GS_TRIP(0, 1); for (int t = 2; t < nt; t += 2) { GS_TRIP(t, 0); } }
;     else { for (int t = 0; t < nt; t += 2) { GS_TRIP(t, 0); } }
	s_waitcnt lgkmcnt(0)
	s_waitcnt lgkmcnt(0)
	v_mfma_f32_16x16x32_f16 v[122:125], v[188:191], v[156:159], v[122:125]
	v_mfma_f32_16x16x32_f16 v[126:129], v[196:199], v[156:159], v[126:129]
	v_mfma_f32_16x16x32_f16 v[106:109], v[188:191], v[164:167], v[106:109]
	v_mfma_f32_16x16x32_f16 v[110:113], v[196:199], v[164:167], v[110:113]
	v_mfma_f32_16x16x32_f16 v[90:93], v[188:191], v[172:175], v[90:93]
	v_mfma_f32_16x16x32_f16 v[94:97], v[196:199], v[172:175], v[94:97]
	v_mfma_f32_16x16x32_f16 v[74:77], v[188:191], v[180:183], v[74:77]
	v_mfma_f32_16x16x32_f16 v[78:81], v[196:199], v[180:183], v[78:81]
	v_mfma_f32_16x16x32_f16 v[122:125], v[192:195], v[160:163], v[122:125]
	v_mfma_f32_16x16x32_f16 v[126:129], v[200:203], v[160:163], v[126:129]
	v_mfma_f32_16x16x32_f16 v[106:109], v[192:195], v[168:171], v[106:109]
	v_mfma_f32_16x16x32_f16 v[110:113], v[200:203], v[168:171], v[110:113]
	v_mfma_f32_16x16x32_f16 v[90:93], v[192:195], v[176:179], v[90:93]
	v_mfma_f32_16x16x32_f16 v[94:97], v[200:203], v[176:179], v[94:97]
	v_mfma_f32_16x16x32_f16 v[74:77], v[192:195], v[184:187], v[74:77]
	v_mfma_f32_16x16x32_f16 v[78:81], v[200:203], v[184:187], v[78:81]
	s_mov_b32 m0, s72
	v_lshl_add_u64 v[208:209], v[206:207], 0, s[24:25]
	s_barrier
	ds_read_b128 v[156:159], v141 offset:49152
	ds_read_b128 v[160:163], v141 offset:50176
	ds_read_b128 v[164:167], v141 offset:51200
	ds_read_b128 v[168:171], v141 offset:52224
	ds_read_b128 v[172:175], v141 offset:53248
	ds_read_b128 v[176:179], v141 offset:54272
	ds_read_b128 v[180:183], v141 offset:55296
	ds_read_b128 v[184:187], v141 offset:56320
	global_load_lds_dwordx4 v[208:209], off
	v_lshl_add_u64 v[206:207], v[206:207], 0, s[28:29]
	s_mov_b32 m0, s73
	s_nop 0
	global_load_lds_dwordx4 v[206:207], off
	s_barrier
	s_waitcnt lgkmcnt(0)
	s_waitcnt lgkmcnt(0)
	v_mfma_f32_16x16x32_f16 v[58:61], v[136:139], v[156:159], v[58:61]
	v_mfma_f32_16x16x32_f16 v[50:53], v[148:151], v[156:159], v[50:53]
	v_mfma_f32_16x16x32_f16 v[38:41], v[136:139], v[164:167], v[38:41]
	v_mfma_f32_16x16x32_f16 v[34:37], v[148:151], v[164:167], v[34:37]
	v_mfma_f32_16x16x32_f16 v[22:25], v[136:139], v[172:175], v[22:25]
	v_mfma_f32_16x16x32_f16 v[18:21], v[148:151], v[172:175], v[18:21]
	v_mfma_f32_16x16x32_f16 v[10:13], v[136:139], v[180:183], v[10:13]
	v_mfma_f32_16x16x32_f16 v[6:9], v[148:151], v[180:183], v[6:9]
	v_mfma_f32_16x16x32_f16 v[58:61], v[144:147], v[160:163], v[58:61]
	v_mfma_f32_16x16x32_f16 v[50:53], v[152:155], v[160:163], v[50:53]
	v_mfma_f32_16x16x32_f16 v[38:41], v[144:147], v[168:171], v[38:41]
	v_mfma_f32_16x16x32_f16 v[34:37], v[152:155], v[168:171], v[34:37]
	v_mfma_f32_16x16x32_f16 v[22:25], v[144:147], v[176:179], v[22:25]
	v_mfma_f32_16x16x32_f16 v[18:21], v[152:155], v[176:179], v[18:21]
	v_mfma_f32_16x16x32_f16 v[10:13], v[144:147], v[184:187], v[10:13]
	v_mfma_f32_16x16x32_f16 v[6:9], v[152:155], v[184:187], v[6:9]
	s_barrier
	s_mov_b32 m0, s74
	v_lshl_add_u64 v[136:137], v[204:205], 0, s[30:31]
	global_load_lds_dwordx4 v[136:137], off
	v_lshl_add_u64 v[136:137], v[204:205], 0, s[28:29]
	s_mov_b32 m0, s75
	s_nop 0
	global_load_lds_dwordx4 v[136:137], off
	s_waitcnt vmcnt(6)
	s_barrier
	v_mfma_f32_16x16x32_f16 v[62:65], v[188:191], v[156:159], v[62:65]
	v_mfma_f32_16x16x32_f16 v[70:73], v[196:199], v[156:159], v[70:73]
	v_mfma_f32_16x16x32_f16 v[42:45], v[188:191], v[164:167], v[42:45]
	v_mfma_f32_16x16x32_f16 v[46:49], v[196:199], v[164:167], v[46:49]
	v_mfma_f32_16x16x32_f16 v[26:29], v[188:191], v[172:175], v[26:29]
	v_mfma_f32_16x16x32_f16 v[30:33], v[196:199], v[172:175], v[30:33]
	v_mfma_f32_16x16x32_f16 v[14:17], v[188:191], v[180:183], v[14:17]
	v_mfma_f32_16x16x32_f16 v[2:5], v[196:199], v[180:183], v[2:5]
	v_mfma_f32_16x16x32_f16 v[62:65], v[192:195], v[160:163], v[62:65]
	v_mfma_f32_16x16x32_f16 v[70:73], v[200:203], v[160:163], v[70:73]
	v_mfma_f32_16x16x32_f16 v[42:45], v[192:195], v[168:171], v[42:45]
	v_mfma_f32_16x16x32_f16 v[46:49], v[200:203], v[168:171], v[46:49]
	v_mfma_f32_16x16x32_f16 v[26:29], v[192:195], v[176:179], v[26:29]
	v_mfma_f32_16x16x32_f16 v[30:33], v[200:203], v[176:179], v[30:33]
	v_mfma_f32_16x16x32_f16 v[14:17], v[192:195], v[184:187], v[14:17]
	v_mfma_f32_16x16x32_f16 v[2:5], v[200:203], v[184:187], v[2:5]
	s_add_i32 s85, s85, 2
	s_add_u32 s44, s44, 0x100
	s_addc_u32 s45, s45, 0
	s_add_u32 s51, s51, 0x100
	s_addc_u32 s84, s84, 0
	s_cmp_gt_u32 s85, 29
	s_barrier
	s_cbranch_scc1 .LBB0_846
